# combined: merge epilogue running-sum load hoist + GEMM progressive lgkmcnt waits + attention early K reads + packed f32 row-sum (v_pk_add_f32, loop 1 first half)
# speedup vs baseline: 1.0098x; 1.0040x over previous
; #define SBAR() __builtin_amdgcn_sched_barrier(0)
; #define SLOAD(i, k0) do { sr_[i].vs0 = *reinterpret_cast<const bf16x8*>(&Vh[(size_t)((k0) + sr) * 128 + sc]); sr_[i].vs1 = *reinterpret_cast<const bf16x8*>(&Vh[(size_t)((k0) + 32 + sr) * 128 + sc]); \
;     sr_[i].ks0 = *reinterpret_cast<const bf16x8*>(&Kh[(size_t)((k0) + kr) * 64 + kc]); } while (0)
; #define SWRITE(b, i) do { *(bf16x8*)(V_lds + (b) * AT_SHM_V + vst0) = sr_[i].vs0; *(bf16x8*)(V_lds + (b) * AT_SHM_V + vst1) = sr_[i].vs1; \
;     *(bf16x8*)(K_lds + (b) * AT_SHM_K + kst) = sr_[i].ks0; } while (0)
; #define SWAIT() asm volatile("s_waitcnt vmcnt(3)" ::: "memory")
; DEV void finishSM(f32x16& p0, f32x16& p1, float alpha, float& l_reg, bf16x8& pa0, bf16x8& pa1, bf16x8& pa2, bf16x8& pa3) {
;     ...
;   for (int r = 0; r < 16; ++r) p1[r] = __builtin_amdgcn_exp2f(p1[r]);
;   float ps = 0;
; #pragma unroll
;   for (int r = 0; r < 16; ++r) ps += p0[r];
; #pragma unroll
;   for (int r = 0; r < 16; ++r) ps += p1[r];
;   { auto rr = __builtin_amdgcn_permlane32_swap(__float_as_uint(ps), __float_as_uint(ps), false, false);
;     ps = __uint_as_float(rr[0]) + __uint_as_float(rr[1]); }
;   l_reg = l_reg * alpha + ps;
;     ...
;   PK4(p0, 0, pa0); PK4(p0, 8, pa1); PK4(p1, 0, pa2); PK4(p1, 8, pa3);
; DEV void attn_pass(const u16* __restrict__ Qb, const u16* __restrict__ Kh, const u16* __restrict__ Vh, int seq, f32x16* o, float* rli) {
;     ...
;     SBAR(); qkt(pB0, pB1, K_lds + b0 * AT_SHM_K, qr, r32, hi);
;     finishSM(pA0, pA1, alA, l_reg, pa0, pa1, pa2, pa3); SBAR();
;     SLOAD(SO, (j + 2) * 64); SBAR();
;     pv_d0(o, vb0 + bm1 * AT_SHM_V, pa0, pa1, pa2, pa3); partialSM(pB0, pB1, m_reg, mnB, alB);
;     SWAIT(); SWRITE(b1, SE);
.LBB0_70:
	s_mul_hi_u32 s1, s9, 0xaaaaaaab
	s_lshr_b32 s1, s1, 1
	s_mul_i32 s1, s1, 0xc000
	v_subrev_u32_e32 v190, s1, v184
	s_mul_hi_u32 s1, s51, 0xaaaaaaab
	s_mul_hi_u32 s0, s66, 0xaaaaaaab
	s_lshr_b32 s12, s1, 1
	s_lshr_b32 s0, s0, 1
	s_mul_i32 s1, s12, 0x6000
	s_mul_i32 s15, s0, 0x6000
	v_subrev_u32_e32 v64, s1, v198
	s_mul_i32 s0, s0, 0xc000
	v_subrev_u32_e32 v216, s15, v180
	v_subrev_u32_e32 v164, s1, v200
	v_subrev_u32_e32 v217, s0, v203
	v_subrev_u32_e32 v218, s0, v204
	v_subrev_u32_e32 v191, s1, v209
	v_subrev_u32_e32 v192, s1, v210
	v_add_u32_e32 v141, s14, v181
	v_add_u32_e32 v68, v141, v64
	ds_read_b128 v[64:67], v68
	ds_read_b128 v[68:71], v68 offset:4096
	v_add_u32_e32 v186, v141, v164
	ds_read_b128 v[164:167], v186
	ds_read_b128 v[186:189], v186 offset:4096
	s_waitcnt vmcnt(0)
	v_add_u32_e32 v72, s8, v202
	v_add_u32_e32 v73, v72, v218
	ds_write_b128 v73, v[116:119]
	v_add_u32_e32 v73, v72, v217
	s_add_i32 s13, s14, 0
	ds_write_b128 v73, v[112:115]
	v_add_u32_e32 v73, s13, v216
	ds_write_b128 v73, v[120:123]
	v_exp_f32_e32 v134, v134
	s_waitcnt lgkmcnt(6)
	v_mfma_f32_32x32x16_bf16 v[80:95], v[64:67], v[108:111], v[236:251]
	v_exp_f32_e32 v135, v135
	v_exp_f32_e32 v132, v132
	v_exp_f32_e32 v133, v133
	v_exp_f32_e32 v130, v130
	v_exp_f32_e32 v131, v131
	v_exp_f32_e32 v128, v128
	v_exp_f32_e32 v129, v129
	s_waitcnt lgkmcnt(5)
	v_mfma_f32_32x32x16_bf16 v[64:79], v[68:71], v[108:111], v[236:251]
	v_exp_f32_e32 v126, v126
	v_exp_f32_e32 v127, v127
	v_exp_f32_e32 v124, v124
	v_exp_f32_e32 v125, v125
	s_waitcnt lgkmcnt(4)
	v_mfma_f32_32x32x16_bf16 v[80:95], v[164:167], v[104:107], v[80:95]
	s_waitcnt lgkmcnt(3)
	v_mfma_f32_32x32x16_bf16 v[64:79], v[186:189], v[104:107], v[64:79]
	v_add_u32_e32 v186, v141, v191
	ds_read_b128 v[164:167], v186
	ds_read_b128 v[186:189], v186 offset:4096
	s_waitcnt lgkmcnt(1)
	v_mfma_f32_32x32x16_bf16 v[80:95], v[164:167], v[100:103], v[80:95]
	s_waitcnt lgkmcnt(0)
	v_mfma_f32_32x32x16_bf16 v[64:79], v[186:189], v[100:103], v[64:79]
	v_add_u32_e32 v186, v141, v192
	ds_read_b128 v[164:167], v186
	ds_read_b128 v[186:189], v186 offset:4096
	s_waitcnt lgkmcnt(1)
	v_mfma_f32_32x32x16_bf16 v[80:95], v[164:167], v[96:99], v[80:95]
	v_exp_f32_e32 v166, v136
	v_exp_f32_e32 v164, v138
	v_exp_f32_e32 v165, v139
	v_exp_f32_e32 v167, v137
	v_mov_b64_e32 v[136:137], v[150:151]
	v_pk_add_f32 v[136:137], v[136:137], v[160:161]
	v_pk_add_f32 v[136:137], v[136:137], v[158:159]
	v_pk_add_f32 v[136:137], v[136:137], v[214:215]
	v_pk_add_f32 v[136:137], v[136:137], v[142:143]
	v_pk_add_f32 v[136:137], v[136:137], v[146:147]
	v_pk_add_f32 v[136:137], v[136:137], v[144:145]
	v_pk_add_f32 v[136:137], v[136:137], v[148:149]
	v_pk_add_f32 v[136:137], v[136:137], v[164:165]
	v_pk_add_f32 v[136:137], v[136:137], v[166:167]
	v_pk_add_f32 v[136:137], v[136:137], v[134:135]
	v_pk_add_f32 v[136:137], v[136:137], v[132:133]
	v_pk_add_f32 v[136:137], v[136:137], v[130:131]
	s_waitcnt lgkmcnt(0)
	v_mfma_f32_32x32x16_bf16 v[64:79], v[186:189], v[96:99], v[64:79]
	v_pk_add_f32 v[136:137], v[136:137], v[128:129]
	v_pk_add_f32 v[136:137], v[136:137], v[126:127]
	v_pk_add_f32 v[136:137], v[136:137], v[124:125]
	v_add_f32_e32 v211, v136, v137
	v_mov_b32_e32 v212, v211
	v_cvt_pk_bf16_f32 v136, v150, v160
	v_cvt_pk_bf16_f32 v138, v158, v214
	s_nop 1
	v_permlane32_swap_b32_e32 v211, v212
	v_cvt_pk_bf16_f32 v137, v151, v161
	v_cvt_pk_bf16_f32 v139, v159, v215
	v_permlane32_swap_b32_e32 v136, v138
	v_cvt_pk_bf16_f32 v142, v142, v146
	v_cvt_pk_bf16_f32 v143, v143, v147
	v_cvt_pk_bf16_f32 v144, v144, v148
	v_cvt_pk_bf16_f32 v145, v145, v149
	v_cvt_pk_bf16_f32 v146, v164, v165
	v_cvt_pk_bf16_f32 v147, v166, v167
	v_cvt_pk_bf16_f32 v148, v134, v135
	v_cvt_pk_bf16_f32 v149, v132, v133
	v_cvt_pk_bf16_f32 v164, v130, v131
	v_cvt_pk_bf16_f32 v165, v128, v129
	v_cvt_pk_bf16_f32 v166, v126, v127
	v_cvt_pk_bf16_f32 v167, v124, v125
	v_permlane32_swap_b32_e32 v137, v139
	v_permlane32_swap_b32_e32 v142, v144
	v_permlane32_swap_b32_e32 v143, v145
	v_permlane32_swap_b32_e32 v146, v148
	v_permlane32_swap_b32_e32 v147, v149
	v_permlane32_swap_b32_e32 v164, v166
	v_permlane32_swap_b32_e32 v165, v167
	v_lshl_add_u64 v[158:159], v[156:157], 0, s[82:83]
	v_add_co_u32_e32 v124, vcc, s94, v158
	v_lshl_add_u64 v[160:161], v[154:155], 0, s[82:83]
	s_nop 0
	v_addc_co_u32_e32 v125, vcc, 0, v159, vcc
	v_add_co_u32_e32 v128, vcc, s95, v158
	s_mov_b32 s0, 0x18606000
	s_nop 0
	v_addc_co_u32_e32 v129, vcc, 0, v159, vcc
	v_add_co_u32_e32 v132, vcc, s0, v160
	global_load_dwordx4 v[124:127], v[124:125], off
	s_nop 0
	global_load_dwordx4 v[128:131], v[128:129], off
	v_addc_co_u32_e32 v133, vcc, 0, v161, vcc
	global_load_dwordx4 v[132:135], v[132:133], off
	v_add_u32_e32 v150, s8, v190
	ds_read_b64_tr_b16 v[186:187], v150 offset:0
	ds_read_b64_tr_b16 v[188:189], v150 offset:0x800
	ds_read_b64_tr_b16 v[190:191], v150 offset:0x1000
	ds_read_b64_tr_b16 v[192:193], v150 offset:0x1800
	ds_read_b64_tr_b16 v[220:221], v150 offset:0x2000
	ds_read_b64_tr_b16 v[222:223], v150 offset:0x2800
	ds_read_b64_tr_b16 v[224:225], v150 offset:0x3000
	ds_read_b64_tr_b16 v[226:227], v150 offset:0x3800
	s_waitcnt lgkmcnt(0)
; #define SBAR() __builtin_amdgcn_sched_barrier(0)
; DEV void partialSM(f32x16& p0, f32x16& p1, float& m_reg, float& mn, float& alpha) {
;   constexpr float C = AT_SCALE * 1.4426950408889634f;
;   float pmax = p0[0];
; #pragma unroll
;   for (int r = 1; r < 16; ++r) pmax = fmaxf(pmax, p0[r]);
; #pragma unroll
;   for (int r = 0; r < 16; ++r) pmax = fmaxf(pmax, p1[r]);
;   { auto rr = __builtin_amdgcn_permlane32_swap(__float_as_uint(pmax), __float_as_uint(pmax), false, false);
;     pmax = fmaxf(__uint_as_float(rr[0]), __uint_as_float(rr[1])); }
;   if (__builtin_expect(__all(pmax - m_reg <= AT_THR / AT_SCALE), 1)) { mn = m_reg; alpha = 1.f; }
;   else { mn = fmaxf(m_reg, pmax); alpha = __builtin_amdgcn_exp2f((m_reg - mn) * C); m_reg = mn; }
; template <int D0> DEV void pv_one(f32x16& od, int vb, bf16x8 pa0, bf16x8 pa1, bf16x8 pa2, bf16x8 pa3) {
;   const s16x4 l0 = tr_read<v_rd_off(D0, 0, 0)>(vb), h0 = tr_read<v_rd_off(D0, 0, 1)>(vb), l1 = tr_read<v_rd_off(D0, 1, 0)>(vb), h1 = tr_read<v_rd_off(D0, 1, 1)>(vb);
;   const s16x4 l2 = tr_read<v_rd_off(D0, 2, 0)>(vb), h2 = tr_read<v_rd_off(D0, 2, 1)>(vb), l3 = tr_read<v_rd_off(D0, 3, 0)>(vb), h3 = tr_read<v_rd_off(D0, 3, 1)>(vb);
;   asm volatile("s_waitcnt lgkmcnt(0)" ::: "memory"); SBAR();
;     ...
;   od = __builtin_amdgcn_mfma_f32_32x32x16_bf16(pa0, PK(l0, h0), od, 0, 0, 0);
;   od = __builtin_amdgcn_mfma_f32_32x32x16_bf16(pa1, PK(l1, h1), od, 0, 0, 0);
;   od = __builtin_amdgcn_mfma_f32_32x32x16_bf16(pa2, PK(l2, h2), od, 0, 0, 0);
;   od = __builtin_amdgcn_mfma_f32_32x32x16_bf16(pa3, PK(l3, h3), od, 0, 0, 0);
;     ...
; }
; DEV void pv_d0(f32x16* o, int vb, bf16x8 pa0, bf16x8 pa1, bf16x8 pa2, bf16x8 pa3) {
;   pv_one<0>(o[0], vb, pa0, pa1, pa2, pa3); pv_one<1>(o[1], vb, pa0, pa1, pa2, pa3); pv_one<2>(o[2], vb, pa0, pa1, pa2, pa3); pv_one<3>(o[3], vb, pa0, pa1, pa2, pa3);
; }
	s_nop 0
	v_mfma_f32_32x32x16_bf16 v[0:15], v[136:139], v[186:189], v[0:15]
	ds_read_b64_tr_b16 v[186:187], v150 offset:0x200
	ds_read_b64_tr_b16 v[188:189], v150 offset:0xa00
	v_mfma_f32_32x32x16_bf16 v[0:15], v[142:145], v[190:193], v[0:15]
	ds_read_b64_tr_b16 v[190:191], v150 offset:0x1200
	ds_read_b64_tr_b16 v[192:193], v150 offset:0x1a00
	v_mfma_f32_32x32x16_bf16 v[0:15], v[146:149], v[220:223], v[0:15]
	ds_read_b64_tr_b16 v[220:221], v150 offset:0x2200
	ds_read_b64_tr_b16 v[222:223], v150 offset:0x2a00
	v_mfma_f32_32x32x16_bf16 v[0:15], v[164:167], v[224:227], v[0:15]
	ds_read_b64_tr_b16 v[224:225], v150 offset:0x3200
	ds_read_b64_tr_b16 v[226:227], v150 offset:0x3a00
	s_waitcnt lgkmcnt(0)
	v_mfma_f32_32x32x16_bf16 v[48:63], v[136:139], v[186:189], v[48:63]
	ds_read_b64_tr_b16 v[186:187], v150 offset:0x400
	ds_read_b64_tr_b16 v[188:189], v150 offset:0xc00
	v_mfma_f32_32x32x16_bf16 v[48:63], v[142:145], v[190:193], v[48:63]
	ds_read_b64_tr_b16 v[190:191], v150 offset:0x1400
	ds_read_b64_tr_b16 v[192:193], v150 offset:0x1c00
	v_mfma_f32_32x32x16_bf16 v[48:63], v[146:149], v[220:223], v[48:63]
	ds_read_b64_tr_b16 v[220:221], v150 offset:0x2400
	ds_read_b64_tr_b16 v[222:223], v150 offset:0x2c00
	v_mfma_f32_32x32x16_bf16 v[48:63], v[164:167], v[224:227], v[48:63]
	ds_read_b64_tr_b16 v[224:225], v150 offset:0x3400
	ds_read_b64_tr_b16 v[226:227], v150 offset:0x3c00
	s_waitcnt lgkmcnt(0)
	v_mfma_f32_32x32x16_bf16 v[32:47], v[136:139], v[186:189], v[32:47]
	ds_read_b64_tr_b16 v[186:187], v150 offset:0x600
	ds_read_b64_tr_b16 v[188:189], v150 offset:0xe00
	v_mfma_f32_32x32x16_bf16 v[32:47], v[142:145], v[190:193], v[32:47]
	ds_read_b64_tr_b16 v[190:191], v150 offset:0x1600
	ds_read_b64_tr_b16 v[192:193], v150 offset:0x1e00
	v_mfma_f32_32x32x16_bf16 v[32:47], v[146:149], v[220:223], v[32:47]
	ds_read_b64_tr_b16 v[220:221], v150 offset:0x2600
	ds_read_b64_tr_b16 v[222:223], v150 offset:0x2e00
	v_mfma_f32_32x32x16_bf16 v[32:47], v[164:167], v[224:227], v[32:47]
	ds_read_b64_tr_b16 v[224:225], v150 offset:0x3600
	ds_read_b64_tr_b16 v[226:227], v150 offset:0x3e00
	s_waitcnt lgkmcnt(0)
	v_mfma_f32_32x32x16_bf16 v[16:31], v[136:139], v[186:189], v[16:31]
	v_max_f32_e32 v136, v80, v81
	v_max3_f32 v137, v64, v65, v66
	v_max3_f32 v136, v136, v82, v83
	v_max3_f32 v137, v137, v67, v68
	v_max3_f32 v136, v136, v84, v85
	v_max3_f32 v137, v137, v69, v70
	v_max3_f32 v136, v136, v86, v87
	v_max3_f32 v137, v137, v71, v72
	v_mfma_f32_32x32x16_bf16 v[16:31], v[142:145], v[190:193], v[16:31]
	v_max3_f32 v136, v136, v88, v89
	v_max3_f32 v137, v137, v73, v74
	v_max3_f32 v136, v136, v90, v91
	v_max3_f32 v137, v137, v75, v76
	v_max3_f32 v136, v136, v92, v93
	v_max3_f32 v137, v137, v77, v78
	v_max3_f32 v136, v136, v94, v95
	v_max3_f32 v136, v136, v137, v79
	v_mfma_f32_32x32x16_bf16 v[16:31], v[146:149], v[220:223], v[16:31]
	v_mov_b32_e32 v137, v136
	s_nop 1
	v_permlane32_swap_b32_e32 v136, v137
	v_max_f32_e32 v136, v136, v137
	v_cmp_ge_f32_e32 vcc, s18, v136
	v_mfma_f32_32x32x16_bf16 v[16:31], v[164:167], v[224:227], v[16:31]
	s_cmp_eq_u64 vcc, exec
	s_cselect_b64 s[0:1], -1, 0
	s_cbranch_scc1 .Lattn_fast1
	v_max_f32_e32 v136, 0, v136
	v_exp_f32_e64 v137, -v136
